# code placement: MODE0 steady attention loop steps each shifted by 4 bytes (83 of 123 eight-byte instructions now 8-byte aligned, was 63)
# speedup vs baseline: 1.0001x; 1.0001x over previous
.LBB0_798:
	s_nop 0
	v_add_u32_e32 v197, s10, v219
	ds_read_b64_tr_b16 v[184:185], v197 offset:24576
	ds_read_b64_tr_b16 v[186:187], v197 offset:25088
	v_mfma_f32_32x32x16_bf16 v[100:115], v[180:183], v[116:119], v[36:51]
	v_add_f32_e32 v84, v68, v69
	v_add_f32_e32 v84, v70, v84
	v_add_f32_e32 v84, v71, v84
	v_cvt_pk_bf16_f32 v148, v68, v69
	v_add_f32_e32 v84, v72, v84
	v_cvt_pk_bf16_f32 v149, v70, v71
	v_add_f32_e32 v84, v73, v84
	ds_read_b64_tr_b16 v[180:181], v197 offset:28672
	ds_read_b64_tr_b16 v[182:183], v197 offset:29184
	v_add_f32_e32 v68, v74, v84
	v_mfma_f32_32x32x16_bf16 v[84:99], v[176:179], v[116:119], v[36:51]
	v_add_f32_e32 v68, v75, v68
	v_add_f32_e32 v68, v76, v68
	v_add_f32_e32 v136, v77, v68
	v_cvt_pk_bf16_f32 v150, v72, v73
	v_cvt_pk_bf16_f32 v151, v74, v75
	ds_read_b64_tr_b16 v[68:69], v197 offset:25600
	ds_read_b64_tr_b16 v[70:71], v197 offset:26112
	v_mfma_f32_32x32x16_bf16 v[100:115], v[172:175], v[120:123], v[100:115]
	v_add_f32_e32 v72, v78, v136
	v_add_f32_e32 v72, v79, v72
	v_add_f32_e32 v72, v80, v72
	v_add_f32_e32 v136, v81, v72
	v_cvt_pk_bf16_f32 v144, v76, v77
	v_cvt_pk_bf16_f32 v145, v78, v79
	ds_read_b64_tr_b16 v[72:73], v197 offset:29696
	ds_read_b64_tr_b16 v[74:75], v197 offset:30208
	v_mfma_f32_32x32x16_bf16 v[84:99], v[168:171], v[120:123], v[84:99]
	v_add_f32_e32 v76, v82, v136
	v_add_f32_e32 v76, v83, v76
	v_add_f32_e32 v76, v52, v76
	v_add_f32_e32 v136, v53, v76
	v_cvt_pk_bf16_f32 v146, v80, v81
	v_cvt_pk_bf16_f32 v147, v82, v83
	ds_read_b64_tr_b16 v[76:77], v197 offset:26624
	ds_read_b64_tr_b16 v[78:79], v197 offset:27136
	v_mfma_f32_32x32x16_bf16 v[100:115], v[164:167], v[124:127], v[100:115]
	v_add_f32_e32 v80, v54, v136
	v_add_f32_e32 v80, v55, v80
	v_cvt_pk_bf16_f32 v140, v52, v53
	v_add_f32_e32 v80, v56, v80
	v_cvt_pk_bf16_f32 v141, v54, v55
	v_add_f32_e32 v80, v57, v80
	ds_read_b64_tr_b16 v[52:53], v197 offset:30720
	ds_read_b64_tr_b16 v[54:55], v197 offset:31232
	v_mfma_f32_32x32x16_bf16 v[84:99], v[160:163], v[124:127], v[84:99]
	v_add_f32_e32 v80, v58, v80
	v_add_f32_e32 v80, v59, v80
	v_cvt_pk_bf16_f32 v142, v56, v57
	v_add_f32_e32 v80, v60, v80
	v_cvt_pk_bf16_f32 v143, v58, v59
	v_add_f32_e32 v80, v61, v80
	ds_read_b64_tr_b16 v[56:57], v197 offset:27648
	ds_read_b64_tr_b16 v[58:59], v197 offset:28160
	v_mfma_f32_32x32x16_bf16 v[100:115], v[156:159], v[128:131], v[100:115]
	v_add_f32_e32 v80, v62, v80
	v_add_f32_e32 v80, v63, v80
	v_cvt_pk_bf16_f32 v136, v60, v61
	v_add_f32_e32 v80, v64, v80
	v_cvt_pk_bf16_f32 v137, v62, v63
	v_add_f32_e32 v80, v65, v80
	ds_read_b64_tr_b16 v[60:61], v197 offset:31744
	ds_read_b64_tr_b16 v[62:63], v197 offset:32256
	v_mfma_f32_32x32x16_bf16 v[84:99], v[152:155], v[128:131], v[84:99]
	v_add_f32_e32 v80, v66, v80
	v_cvt_pk_bf16_f32 v138, v64, v65
	v_add_f32_e32 v80, v67, v80
	v_cvt_pk_bf16_f32 v139, v66, v67
	s_add_i32 s10, s25, s46
	s_mov_b32 m0, s10
	s_nop 0
	global_load_lds_dwordx4 v202, s[98:99]
	s_add_i32 s10, s24, s47
	s_mov_b32 m0, s10
	s_nop 0
	global_load_lds_dwordx4 v203, s[98:99]
	v_add_f32_e32 v204, v220, v80

.LBB0_801:
	s_nop 0
	v_add_u32_e32 v197, s25, v219
	ds_read_b64_tr_b16 v[152:153], v197 offset:24576
	ds_read_b64_tr_b16 v[154:155], v197 offset:25088
	v_mfma_f32_32x32x16_bf16 v[68:83], v[64:67], v[116:119], v[36:51]
	v_add_f32_e32 v52, v100, v101
	v_add_f32_e32 v52, v102, v52
	v_add_f32_e32 v52, v103, v52
	v_cvt_pk_bf16_f32 v148, v100, v101
	v_add_f32_e32 v52, v104, v52
	v_cvt_pk_bf16_f32 v149, v102, v103
	v_add_f32_e32 v52, v105, v52
	ds_read_b64_tr_b16 v[156:157], v197 offset:28672
	ds_read_b64_tr_b16 v[158:159], v197 offset:29184
	v_add_f32_e32 v52, v106, v52
	v_add_f32_e32 v52, v107, v52
	v_add_f32_e32 v52, v108, v52
	v_add_f32_e32 v136, v109, v52
	v_mfma_f32_32x32x16_bf16 v[52:67], v[180:183], v[116:119], v[36:51]
	v_cvt_pk_bf16_f32 v150, v104, v105
	v_cvt_pk_bf16_f32 v151, v106, v107
	ds_read_b64_tr_b16 v[100:101], v197 offset:25600
	ds_read_b64_tr_b16 v[102:103], v197 offset:26112
	v_mfma_f32_32x32x16_bf16 v[68:83], v[184:187], v[120:123], v[68:83]
	v_add_f32_e32 v104, v110, v136
	v_add_f32_e32 v104, v111, v104
	v_add_f32_e32 v104, v112, v104
	v_add_f32_e32 v136, v113, v104
	v_cvt_pk_bf16_f32 v144, v108, v109
	v_cvt_pk_bf16_f32 v145, v110, v111
	ds_read_b64_tr_b16 v[104:105], v197 offset:29696
	ds_read_b64_tr_b16 v[106:107], v197 offset:30208
	v_mfma_f32_32x32x16_bf16 v[52:67], v[176:179], v[120:123], v[52:67]
	v_add_f32_e32 v108, v114, v136
	v_add_f32_e32 v108, v115, v108
	v_add_f32_e32 v108, v84, v108
	v_add_f32_e32 v136, v85, v108
	v_cvt_pk_bf16_f32 v146, v112, v113
	v_cvt_pk_bf16_f32 v147, v114, v115
	ds_read_b64_tr_b16 v[108:109], v197 offset:26624
	ds_read_b64_tr_b16 v[110:111], v197 offset:27136
	v_mfma_f32_32x32x16_bf16 v[68:83], v[172:175], v[124:127], v[68:83]
	v_add_f32_e32 v112, v86, v136
	v_add_f32_e32 v112, v87, v112
	v_cvt_pk_bf16_f32 v140, v84, v85
	v_add_f32_e32 v112, v88, v112
	v_cvt_pk_bf16_f32 v141, v86, v87
	v_add_f32_e32 v112, v89, v112
	ds_read_b64_tr_b16 v[84:85], v197 offset:30720
	ds_read_b64_tr_b16 v[86:87], v197 offset:31232
	v_mfma_f32_32x32x16_bf16 v[52:67], v[168:171], v[124:127], v[52:67]
	v_add_f32_e32 v112, v90, v112
	v_add_f32_e32 v112, v91, v112
	v_cvt_pk_bf16_f32 v142, v88, v89
	v_add_f32_e32 v112, v92, v112
	v_cvt_pk_bf16_f32 v143, v90, v91
	v_add_f32_e32 v112, v93, v112
	ds_read_b64_tr_b16 v[88:89], v197 offset:27648
	ds_read_b64_tr_b16 v[90:91], v197 offset:28160
	v_mfma_f32_32x32x16_bf16 v[68:83], v[164:167], v[128:131], v[68:83]
	v_add_f32_e32 v112, v94, v112
	v_add_f32_e32 v112, v95, v112
	v_cvt_pk_bf16_f32 v136, v92, v93
	v_add_f32_e32 v112, v96, v112
	v_cvt_pk_bf16_f32 v137, v94, v95
	v_add_f32_e32 v112, v97, v112
	ds_read_b64_tr_b16 v[92:93], v197 offset:31744
	ds_read_b64_tr_b16 v[94:95], v197 offset:32256
	v_mfma_f32_32x32x16_bf16 v[52:67], v[160:163], v[128:131], v[52:67]
	v_add_f32_e32 v112, v98, v112
	v_cvt_pk_bf16_f32 v138, v96, v97
	v_add_f32_e32 v112, v99, v112
	v_cvt_pk_bf16_f32 v139, v98, v99
	v_add_f32_e32 v220, v204, v112
	s_add_i32 s10, s24, s46
	s_mov_b32 m0, s10
	s_nop 0
	global_load_lds_dwordx4 v198, s[98:99]
	s_add_i32 s10, s54, s47
	s_mov_b32 m0, s10
	s_nop 0
	global_load_lds_dwordx4 v199, s[98:99]
